# v30 + hand-written XN=bf16(x)/row-sum loop: one row per step, three rows of nt loads in flight, DPP wave reduction, write-through stores
# baseline (speedup 1.0000x reference)
; __device__ __forceinline__ void prologue(const Args& a, LAS unsigned char* lds, int wave, int lane) {
;     ...
;     { const float* x = a.in[0]; bf16* XN = (bf16*)(ws + WS_XN); u64* rs0 = (u64*)(ws + WS_ROWSS);
;       for (int m = 2 * gw; m < M; m += 2 * NGW) {
;           const f32x4* xr = (const f32x4*)(x + (size_t)m * D) + lane; f32x4 v[2][4]; float s[2] = {0.f, 0.f};
; #pragma unroll
;           for (int r = 0; r < 2; ++r)
; #pragma unroll
;               for (int j = 0; j < 4; ++j) v[r][j] = xr[r * (D / 4) + 64 * j];
.LBB0_89:
	s_or_b64 exec, exec, s[0:1]
	s_cmp_gt_i32 s11, 0x7fff
	s_cbranch_scc1 .LBB0_98
	v_mov_b32_e32 v1, 0
	v_lshlrev_b32_e32 v2, 4, v200
	v_lshlrev_b32_e32 v3, 3, v200
	s_add_u32 s22, s34, 0x6000000
	s_addc_u32 s23, s35, 0
	s_add_u32 s24, s34, 0x100000
	s_addc_u32 s25, s35, 0
	s_lshl_b32 s1, s28, 3
	s_mov_b32 s0, s11
	s_waitcnt lgkmcnt(0)
	s_lshl_b32 s2, s0, 12
	s_add_u32 s2, s36, s2
	s_addc_u32 s3, s37, 0
	global_load_dwordx4 v[8:11], v2, s[2:3] offset:0 nt
	global_load_dwordx4 v[12:15], v2, s[2:3] offset:1024 nt
	global_load_dwordx4 v[16:19], v2, s[2:3] offset:2048 nt
	global_load_dwordx4 v[20:23], v2, s[2:3] offset:3072 nt
	s_add_u32 s26, s0, s1
	s_cmp_lt_u32 s26, 0x8000
	s_cbranch_scc0 .Lxn_a
	s_lshl_b32 s2, s26, 12
	s_add_u32 s2, s36, s2
	s_addc_u32 s3, s37, 0
	global_load_dwordx4 v[24:27], v2, s[2:3] offset:0 nt
	global_load_dwordx4 v[28:31], v2, s[2:3] offset:1024 nt
	global_load_dwordx4 v[32:35], v2, s[2:3] offset:2048 nt
	global_load_dwordx4 v[36:39], v2, s[2:3] offset:3072 nt
.Lxn_a:
	s_lshl_b32 s26, s1, 1
	s_add_u32 s26, s0, s26
	s_cmp_lt_u32 s26, 0x8000
	s_cbranch_scc0 .Lxn_a_t
	s_lshl_b32 s2, s26, 12
	s_add_u32 s2, s36, s2
	s_addc_u32 s3, s37, 0
	global_load_dwordx4 v[40:43], v2, s[2:3] offset:0 nt
	global_load_dwordx4 v[44:47], v2, s[2:3] offset:1024 nt
	global_load_dwordx4 v[48:51], v2, s[2:3] offset:2048 nt
	global_load_dwordx4 v[52:55], v2, s[2:3] offset:3072 nt
	s_waitcnt vmcnt(8)
	s_branch .Lxn_a_p

; __device__ __forceinline__ u64 ss_fix(float s) { return (u64)(s * 1099511627776.0f); }
; __device__ __forceinline__ unsigned pk2(float lo, float hi) { return f2bf(lo) | (f2bf(hi) << 16); }
; __device__ __forceinline__ void prologue(const Args& a, LAS unsigned char* lds, int wave, int lane) {
;     ...
;           const f32x4* xr = (const f32x4*)(x + (size_t)m * D) + lane; f32x4 v[2][4]; float s[2] = {0.f, 0.f};
; #pragma unroll
;           for (int r = 0; r < 2; ++r)
; #pragma unroll
;               for (int j = 0; j < 4; ++j) v[r][j] = xr[r * (D / 4) + 64 * j];
; #pragma unroll
;           for (int r = 0; r < 2; ++r) {
; #pragma unroll
;               for (int j = 0; j < 4; ++j) s[r] += (v[r][j][0] * v[r][j][0] + v[r][j][1] * v[r][j][1]) + (v[r][j][2] * v[r][j][2] + v[r][j][3] * v[r][j][3]);
;               s[r] = wave_sum(s[r]); if (lane == 0) rs0[m + r] = ss_fix(s[r]);
;               u32x2* o = (u32x2*)(XN + (size_t)(m + r) * D) + lane;
; #pragma unroll
;               for (int j = 0; j < 4; ++j) { u32x2 w; w.x = pk2(v[r][j][0], v[r][j][1]); w.y = pk2(v[r][j][2], v[r][j][3]); o[64 * j] = w; }
.Lxn_a_p:
	s_lshl_b32 s4, s0, 11
	s_add_u32 s4, s22, s4
	s_addc_u32 s5, s23, 0
	s_lshl_b32 s20, s0, 3
	s_add_u32 s20, s24, s20
	s_addc_u32 s21, s25, 0
	v_mul_f32_e32 v60, v8, v8
	v_fmac_f32_e32 v60, v9, v9
	v_mul_f32_e32 v61, v10, v10
	v_fmac_f32_e32 v61, v11, v11
	v_add_f32_e32 v60, v60, v61
	v_mov_b32_e32 v62, v60
	v_mul_f32_e32 v60, v12, v12
	v_fmac_f32_e32 v60, v13, v13
	v_mul_f32_e32 v61, v14, v14
	v_fmac_f32_e32 v61, v15, v15
	v_add_f32_e32 v60, v60, v61
	v_add_f32_e32 v62, v62, v60
	v_mul_f32_e32 v60, v16, v16
	v_fmac_f32_e32 v60, v17, v17
	v_mul_f32_e32 v61, v18, v18
	v_fmac_f32_e32 v61, v19, v19
	v_add_f32_e32 v60, v60, v61
	v_add_f32_e32 v62, v62, v60
	v_mul_f32_e32 v60, v20, v20
	v_fmac_f32_e32 v60, v21, v21
	v_mul_f32_e32 v61, v22, v22
	v_fmac_f32_e32 v61, v23, v23
	v_add_f32_e32 v60, v60, v61
	v_add_f32_e32 v62, v62, v60
	s_nop 1
	v_add_f32_dpp v62, v62, v62 quad_perm:[1,0,3,2] row_mask:0xf bank_mask:0xf
	s_nop 1
	v_add_f32_dpp v62, v62, v62 quad_perm:[2,3,0,1] row_mask:0xf bank_mask:0xf
	s_nop 1
	v_add_f32_dpp v62, v62, v62 row_half_mirror row_mask:0xf bank_mask:0xf
	s_nop 1
	v_add_f32_dpp v62, v62, v62 row_mirror row_mask:0xf bank_mask:0xf
	s_nop 1
	v_readlane_b32 s38, v62, 0
	v_readlane_b32 s39, v62, 16
	v_readlane_b32 s40, v62, 32
	v_readlane_b32 s41, v62, 48
	s_nop 2
	v_mov_b32_e32 v63, s38
	v_add_f32_e32 v63, s39, v63
	v_add_f32_e32 v63, s40, v63
	v_add_f32_e32 v63, s41, v63
	v_mul_f32_e32 v64, 0x53800000, v63
	v_trunc_f32_e32 v64, v64
	v_mul_f32_e32 v65, 0x2f800000, v64
	v_floor_f32_e32 v65, v65
	v_fmac_f32_e32 v64, 0xcf800000, v65
	v_cvt_u32_f32_e32 v64, v64
	v_cvt_u32_f32_e32 v65, v65
	s_mov_b64 exec, 1
	global_store_dwordx2 v1, v[64:65], s[20:21] sc0 sc1
	s_mov_b64 exec, -1
	v_cvt_pk_bf16_f32 v66, v8, v9
	v_cvt_pk_bf16_f32 v67, v10, v11
	global_store_dwordx2 v3, v[66:67], s[4:5] offset:0 sc0 sc1
	v_cvt_pk_bf16_f32 v68, v12, v13
	v_cvt_pk_bf16_f32 v69, v14, v15
	global_store_dwordx2 v3, v[68:69], s[4:5] offset:512 sc0 sc1
	v_cvt_pk_bf16_f32 v70, v16, v17
	v_cvt_pk_bf16_f32 v71, v18, v19
	global_store_dwordx2 v3, v[70:71], s[4:5] offset:1024 sc0 sc1
	v_cvt_pk_bf16_f32 v72, v20, v21
	v_cvt_pk_bf16_f32 v73, v22, v23
	global_store_dwordx2 v3, v[72:73], s[4:5] offset:1536 sc0 sc1
	s_add_u32 s0, s0, s1
	s_cmp_lt_u32 s0, 0x8000
	s_cbranch_scc0 .LBB0_98
.Lxn_b:
	s_lshl_b32 s26, s1, 1
	s_add_u32 s26, s0, s26
	s_cmp_lt_u32 s26, 0x8000
	s_cbranch_scc0 .Lxn_b_t
	s_lshl_b32 s2, s26, 12
	s_add_u32 s2, s36, s2
	s_addc_u32 s3, s37, 0
	global_load_dwordx4 v[8:11], v2, s[2:3] offset:0 nt
	global_load_dwordx4 v[12:15], v2, s[2:3] offset:1024 nt
	global_load_dwordx4 v[16:19], v2, s[2:3] offset:2048 nt
	global_load_dwordx4 v[20:23], v2, s[2:3] offset:3072 nt
	s_waitcnt vmcnt(13)
	s_branch .Lxn_b_p

; __device__ __forceinline__ u64 ss_fix(float s) { return (u64)(s * 1099511627776.0f); }
; __device__ __forceinline__ unsigned pk2(float lo, float hi) { return f2bf(lo) | (f2bf(hi) << 16); }
; __device__ __forceinline__ void prologue(const Args& a, LAS unsigned char* lds, int wave, int lane) {
;     ...
;           const f32x4* xr = (const f32x4*)(x + (size_t)m * D) + lane; f32x4 v[2][4]; float s[2] = {0.f, 0.f};
; #pragma unroll
;           for (int r = 0; r < 2; ++r)
; #pragma unroll
;               for (int j = 0; j < 4; ++j) v[r][j] = xr[r * (D / 4) + 64 * j];
; #pragma unroll
;           for (int r = 0; r < 2; ++r) {
; #pragma unroll
;               for (int j = 0; j < 4; ++j) s[r] += (v[r][j][0] * v[r][j][0] + v[r][j][1] * v[r][j][1]) + (v[r][j][2] * v[r][j][2] + v[r][j][3] * v[r][j][3]);
;               s[r] = wave_sum(s[r]); if (lane == 0) rs0[m + r] = ss_fix(s[r]);
;               u32x2* o = (u32x2*)(XN + (size_t)(m + r) * D) + lane;
; #pragma unroll
;               for (int j = 0; j < 4; ++j) { u32x2 w; w.x = pk2(v[r][j][0], v[r][j][1]); w.y = pk2(v[r][j][2], v[r][j][3]); o[64 * j] = w; }
.Lxn_b_p:
	s_lshl_b32 s4, s0, 11
	s_add_u32 s4, s22, s4
	s_addc_u32 s5, s23, 0
	s_lshl_b32 s20, s0, 3
	s_add_u32 s20, s24, s20
	s_addc_u32 s21, s25, 0
	v_mul_f32_e32 v60, v24, v24
	v_fmac_f32_e32 v60, v25, v25
	v_mul_f32_e32 v61, v26, v26
	v_fmac_f32_e32 v61, v27, v27
	v_add_f32_e32 v60, v60, v61
	v_mov_b32_e32 v62, v60
	v_mul_f32_e32 v60, v28, v28
	v_fmac_f32_e32 v60, v29, v29
	v_mul_f32_e32 v61, v30, v30
	v_fmac_f32_e32 v61, v31, v31
	v_add_f32_e32 v60, v60, v61
	v_add_f32_e32 v62, v62, v60
	v_mul_f32_e32 v60, v32, v32
	v_fmac_f32_e32 v60, v33, v33
	v_mul_f32_e32 v61, v34, v34
	v_fmac_f32_e32 v61, v35, v35
	v_add_f32_e32 v60, v60, v61
	v_add_f32_e32 v62, v62, v60
	v_mul_f32_e32 v60, v36, v36
	v_fmac_f32_e32 v60, v37, v37
	v_mul_f32_e32 v61, v38, v38
	v_fmac_f32_e32 v61, v39, v39
	v_add_f32_e32 v60, v60, v61
	v_add_f32_e32 v62, v62, v60
	s_nop 1
	v_add_f32_dpp v62, v62, v62 quad_perm:[1,0,3,2] row_mask:0xf bank_mask:0xf
	s_nop 1
	v_add_f32_dpp v62, v62, v62 quad_perm:[2,3,0,1] row_mask:0xf bank_mask:0xf
	s_nop 1
	v_add_f32_dpp v62, v62, v62 row_half_mirror row_mask:0xf bank_mask:0xf
	s_nop 1
	v_add_f32_dpp v62, v62, v62 row_mirror row_mask:0xf bank_mask:0xf
	s_nop 1
	v_readlane_b32 s38, v62, 0
	v_readlane_b32 s39, v62, 16
	v_readlane_b32 s40, v62, 32
	v_readlane_b32 s41, v62, 48
	s_nop 2
	v_mov_b32_e32 v63, s38
	v_add_f32_e32 v63, s39, v63
	v_add_f32_e32 v63, s40, v63
	v_add_f32_e32 v63, s41, v63
	v_mul_f32_e32 v64, 0x53800000, v63
	v_trunc_f32_e32 v64, v64
	v_mul_f32_e32 v65, 0x2f800000, v64
	v_floor_f32_e32 v65, v65
	v_fmac_f32_e32 v64, 0xcf800000, v65
	v_cvt_u32_f32_e32 v64, v64
	v_cvt_u32_f32_e32 v65, v65
	s_mov_b64 exec, 1
	global_store_dwordx2 v1, v[64:65], s[20:21] sc0 sc1
	s_mov_b64 exec, -1
	v_cvt_pk_bf16_f32 v66, v24, v25
	v_cvt_pk_bf16_f32 v67, v26, v27
	global_store_dwordx2 v3, v[66:67], s[4:5] offset:0 sc0 sc1
	v_cvt_pk_bf16_f32 v68, v28, v29
	v_cvt_pk_bf16_f32 v69, v30, v31
	global_store_dwordx2 v3, v[68:69], s[4:5] offset:512 sc0 sc1
	v_cvt_pk_bf16_f32 v70, v32, v33
	v_cvt_pk_bf16_f32 v71, v34, v35
	global_store_dwordx2 v3, v[70:71], s[4:5] offset:1024 sc0 sc1
	v_cvt_pk_bf16_f32 v72, v36, v37
	v_cvt_pk_bf16_f32 v73, v38, v39
	global_store_dwordx2 v3, v[72:73], s[4:5] offset:1536 sc0 sc1
	s_add_u32 s0, s0, s1
	s_cmp_lt_u32 s0, 0x8000
	s_cbranch_scc0 .LBB0_98
.Lxn_c:
	s_lshl_b32 s26, s1, 1
	s_add_u32 s26, s0, s26
	s_cmp_lt_u32 s26, 0x8000
	s_cbranch_scc0 .Lxn_c_t
	s_lshl_b32 s2, s26, 12
	s_add_u32 s2, s36, s2
	s_addc_u32 s3, s37, 0
	global_load_dwordx4 v[24:27], v2, s[2:3] offset:0 nt
	global_load_dwordx4 v[28:31], v2, s[2:3] offset:1024 nt
	global_load_dwordx4 v[32:35], v2, s[2:3] offset:2048 nt
	global_load_dwordx4 v[36:39], v2, s[2:3] offset:3072 nt
	s_waitcnt vmcnt(18)
	s_branch .Lxn_c_p

; __device__ __forceinline__ u64 ss_fix(float s) { return (u64)(s * 1099511627776.0f); }
; __device__ __forceinline__ unsigned pk2(float lo, float hi) { return f2bf(lo) | (f2bf(hi) << 16); }
; __device__ __forceinline__ void prologue(const Args& a, LAS unsigned char* lds, int wave, int lane) {
;     ...
;           const f32x4* xr = (const f32x4*)(x + (size_t)m * D) + lane; f32x4 v[2][4]; float s[2] = {0.f, 0.f};
; #pragma unroll
;           for (int r = 0; r < 2; ++r)
; #pragma unroll
;               for (int j = 0; j < 4; ++j) v[r][j] = xr[r * (D / 4) + 64 * j];
; #pragma unroll
;           for (int r = 0; r < 2; ++r) {
; #pragma unroll
;               for (int j = 0; j < 4; ++j) s[r] += (v[r][j][0] * v[r][j][0] + v[r][j][1] * v[r][j][1]) + (v[r][j][2] * v[r][j][2] + v[r][j][3] * v[r][j][3]);
;               s[r] = wave_sum(s[r]); if (lane == 0) rs0[m + r] = ss_fix(s[r]);
;               u32x2* o = (u32x2*)(XN + (size_t)(m + r) * D) + lane;
; #pragma unroll
;               for (int j = 0; j < 4; ++j) { u32x2 w; w.x = pk2(v[r][j][0], v[r][j][1]); w.y = pk2(v[r][j][2], v[r][j][3]); o[64 * j] = w; }
.Lxn_c_p:
	s_lshl_b32 s4, s0, 11
	s_add_u32 s4, s22, s4
	s_addc_u32 s5, s23, 0
	s_lshl_b32 s20, s0, 3
	s_add_u32 s20, s24, s20
	s_addc_u32 s21, s25, 0
	v_mul_f32_e32 v60, v40, v40
	v_fmac_f32_e32 v60, v41, v41
	v_mul_f32_e32 v61, v42, v42
	v_fmac_f32_e32 v61, v43, v43
	v_add_f32_e32 v60, v60, v61
	v_mov_b32_e32 v62, v60
	v_mul_f32_e32 v60, v44, v44
	v_fmac_f32_e32 v60, v45, v45
	v_mul_f32_e32 v61, v46, v46
	v_fmac_f32_e32 v61, v47, v47
	v_add_f32_e32 v60, v60, v61
	v_add_f32_e32 v62, v62, v60
	v_mul_f32_e32 v60, v48, v48
	v_fmac_f32_e32 v60, v49, v49
	v_mul_f32_e32 v61, v50, v50
	v_fmac_f32_e32 v61, v51, v51
	v_add_f32_e32 v60, v60, v61
	v_add_f32_e32 v62, v62, v60
	v_mul_f32_e32 v60, v52, v52
	v_fmac_f32_e32 v60, v53, v53
	v_mul_f32_e32 v61, v54, v54
	v_fmac_f32_e32 v61, v55, v55
	v_add_f32_e32 v60, v60, v61
	v_add_f32_e32 v62, v62, v60
	s_nop 1
	v_add_f32_dpp v62, v62, v62 quad_perm:[1,0,3,2] row_mask:0xf bank_mask:0xf
	s_nop 1
	v_add_f32_dpp v62, v62, v62 quad_perm:[2,3,0,1] row_mask:0xf bank_mask:0xf
	s_nop 1
	v_add_f32_dpp v62, v62, v62 row_half_mirror row_mask:0xf bank_mask:0xf
	s_nop 1
	v_add_f32_dpp v62, v62, v62 row_mirror row_mask:0xf bank_mask:0xf
	s_nop 1
	v_readlane_b32 s38, v62, 0
	v_readlane_b32 s39, v62, 16
	v_readlane_b32 s40, v62, 32
	v_readlane_b32 s41, v62, 48
	s_nop 2
	v_mov_b32_e32 v63, s38
	v_add_f32_e32 v63, s39, v63
	v_add_f32_e32 v63, s40, v63
	v_add_f32_e32 v63, s41, v63
	v_mul_f32_e32 v64, 0x53800000, v63
	v_trunc_f32_e32 v64, v64
	v_mul_f32_e32 v65, 0x2f800000, v64
	v_floor_f32_e32 v65, v65
	v_fmac_f32_e32 v64, 0xcf800000, v65
	v_cvt_u32_f32_e32 v64, v64
	v_cvt_u32_f32_e32 v65, v65
	s_mov_b64 exec, 1
	global_store_dwordx2 v1, v[64:65], s[20:21] sc0 sc1
	s_mov_b64 exec, -1
	v_cvt_pk_bf16_f32 v66, v40, v41
	v_cvt_pk_bf16_f32 v67, v42, v43
	global_store_dwordx2 v3, v[66:67], s[4:5] offset:0 sc0 sc1
	v_cvt_pk_bf16_f32 v68, v44, v45
	v_cvt_pk_bf16_f32 v69, v46, v47
	global_store_dwordx2 v3, v[68:69], s[4:5] offset:512 sc0 sc1
	v_cvt_pk_bf16_f32 v70, v48, v49
	v_cvt_pk_bf16_f32 v71, v50, v51
	global_store_dwordx2 v3, v[70:71], s[4:5] offset:1024 sc0 sc1
	v_cvt_pk_bf16_f32 v72, v52, v53
	v_cvt_pk_bf16_f32 v73, v54, v55
	global_store_dwordx2 v3, v[72:73], s[4:5] offset:1536 sc0 sc1
	s_add_u32 s0, s0, s1
	s_cmp_lt_u32 s0, 0x8000
	s_cbranch_scc0 .LBB0_98
.Lxn_d:
	s_lshl_b32 s26, s1, 1
	s_add_u32 s26, s0, s26
	s_cmp_lt_u32 s26, 0x8000
	s_cbranch_scc0 .Lxn_d_t
	s_lshl_b32 s2, s26, 12
	s_add_u32 s2, s36, s2
	s_addc_u32 s3, s37, 0
	global_load_dwordx4 v[40:43], v2, s[2:3] offset:0 nt
	global_load_dwordx4 v[44:47], v2, s[2:3] offset:1024 nt
	global_load_dwordx4 v[48:51], v2, s[2:3] offset:2048 nt
	global_load_dwordx4 v[52:55], v2, s[2:3] offset:3072 nt
	s_waitcnt vmcnt(18)
	s_branch .Lxn_d_p

; __device__ __forceinline__ void prologue(const Args& a, LAS unsigned char* lds, int wave, int lane) {
;     ...
;       for (int m = 2 * gw; m < M; m += 2 * NGW) {
;           const f32x4* xr = (const f32x4*)(x + (size_t)m * D) + lane; f32x4 v[2][4]; float s[2] = {0.f, 0.f};
; #pragma unroll
;           for (int r = 0; r < 2; ++r)
; #pragma unroll
;               for (int j = 0; j < 4; ++j) v[r][j] = xr[r * (D / 4) + 64 * j];
.Lxn_e:
	s_lshl_b32 s26, s1, 1
	s_add_u32 s26, s0, s26
	s_cmp_lt_u32 s26, 0x8000
	s_cbranch_scc0 .Lxn_e_t
	s_lshl_b32 s2, s26, 12
	s_add_u32 s2, s36, s2
	s_addc_u32 s3, s37, 0
	global_load_dwordx4 v[8:11], v2, s[2:3] offset:0 nt
	global_load_dwordx4 v[12:15], v2, s[2:3] offset:1024 nt
	global_load_dwordx4 v[16:19], v2, s[2:3] offset:2048 nt
	global_load_dwordx4 v[20:23], v2, s[2:3] offset:3072 nt
	s_waitcnt vmcnt(18)
	s_branch .Lxn_e_p

; __device__ __forceinline__ u64 ss_fix(float s) { return (u64)(s * 1099511627776.0f); }
; __device__ __forceinline__ unsigned pk2(float lo, float hi) { return f2bf(lo) | (f2bf(hi) << 16); }
; __device__ __forceinline__ void prologue(const Args& a, LAS unsigned char* lds, int wave, int lane) {
;     ...
;           const f32x4* xr = (const f32x4*)(x + (size_t)m * D) + lane; f32x4 v[2][4]; float s[2] = {0.f, 0.f};
; #pragma unroll
;           for (int r = 0; r < 2; ++r)
; #pragma unroll
;               for (int j = 0; j < 4; ++j) v[r][j] = xr[r * (D / 4) + 64 * j];
; #pragma unroll
;           for (int r = 0; r < 2; ++r) {
; #pragma unroll
;               for (int j = 0; j < 4; ++j) s[r] += (v[r][j][0] * v[r][j][0] + v[r][j][1] * v[r][j][1]) + (v[r][j][2] * v[r][j][2] + v[r][j][3] * v[r][j][3]);
;               s[r] = wave_sum(s[r]); if (lane == 0) rs0[m + r] = ss_fix(s[r]);
;               u32x2* o = (u32x2*)(XN + (size_t)(m + r) * D) + lane;
; #pragma unroll
;               for (int j = 0; j < 4; ++j) { u32x2 w; w.x = pk2(v[r][j][0], v[r][j][1]); w.y = pk2(v[r][j][2], v[r][j][3]); o[64 * j] = w; }
.Lxn_e_p:
	s_lshl_b32 s4, s0, 11
	s_add_u32 s4, s22, s4
	s_addc_u32 s5, s23, 0
	s_lshl_b32 s20, s0, 3
	s_add_u32 s20, s24, s20
	s_addc_u32 s21, s25, 0
	v_mul_f32_e32 v60, v24, v24
	v_fmac_f32_e32 v60, v25, v25
	v_mul_f32_e32 v61, v26, v26
	v_fmac_f32_e32 v61, v27, v27
	v_add_f32_e32 v60, v60, v61
	v_mov_b32_e32 v62, v60
	v_mul_f32_e32 v60, v28, v28
	v_fmac_f32_e32 v60, v29, v29
	v_mul_f32_e32 v61, v30, v30
	v_fmac_f32_e32 v61, v31, v31
	v_add_f32_e32 v60, v60, v61
	v_add_f32_e32 v62, v62, v60
	v_mul_f32_e32 v60, v32, v32
	v_fmac_f32_e32 v60, v33, v33
	v_mul_f32_e32 v61, v34, v34
	v_fmac_f32_e32 v61, v35, v35
	v_add_f32_e32 v60, v60, v61
	v_add_f32_e32 v62, v62, v60
	v_mul_f32_e32 v60, v36, v36
	v_fmac_f32_e32 v60, v37, v37
	v_mul_f32_e32 v61, v38, v38
	v_fmac_f32_e32 v61, v39, v39
	v_add_f32_e32 v60, v60, v61
	v_add_f32_e32 v62, v62, v60
	s_nop 1
	v_add_f32_dpp v62, v62, v62 quad_perm:[1,0,3,2] row_mask:0xf bank_mask:0xf
	s_nop 1
	v_add_f32_dpp v62, v62, v62 quad_perm:[2,3,0,1] row_mask:0xf bank_mask:0xf
	s_nop 1
	v_add_f32_dpp v62, v62, v62 row_half_mirror row_mask:0xf bank_mask:0xf
	s_nop 1
	v_add_f32_dpp v62, v62, v62 row_mirror row_mask:0xf bank_mask:0xf
	s_nop 1
	v_readlane_b32 s38, v62, 0
	v_readlane_b32 s39, v62, 16
	v_readlane_b32 s40, v62, 32
	v_readlane_b32 s41, v62, 48
	s_nop 2
	v_mov_b32_e32 v63, s38
	v_add_f32_e32 v63, s39, v63
	v_add_f32_e32 v63, s40, v63
	v_add_f32_e32 v63, s41, v63
	v_mul_f32_e32 v64, 0x53800000, v63
	v_trunc_f32_e32 v64, v64
	v_mul_f32_e32 v65, 0x2f800000, v64
	v_floor_f32_e32 v65, v65
	v_fmac_f32_e32 v64, 0xcf800000, v65
	v_cvt_u32_f32_e32 v64, v64
	v_cvt_u32_f32_e32 v65, v65
	s_mov_b64 exec, 1
	global_store_dwordx2 v1, v[64:65], s[20:21] sc0 sc1
	s_mov_b64 exec, -1
	v_cvt_pk_bf16_f32 v66, v24, v25
	v_cvt_pk_bf16_f32 v67, v26, v27
	global_store_dwordx2 v3, v[66:67], s[4:5] offset:0 sc0 sc1
	v_cvt_pk_bf16_f32 v68, v28, v29
	v_cvt_pk_bf16_f32 v69, v30, v31
	global_store_dwordx2 v3, v[68:69], s[4:5] offset:512 sc0 sc1
	v_cvt_pk_bf16_f32 v70, v32, v33
	v_cvt_pk_bf16_f32 v71, v34, v35
	global_store_dwordx2 v3, v[70:71], s[4:5] offset:1024 sc0 sc1
	v_cvt_pk_bf16_f32 v72, v36, v37
	v_cvt_pk_bf16_f32 v73, v38, v39
	global_store_dwordx2 v3, v[72:73], s[4:5] offset:1536 sc0 sc1
	s_add_u32 s0, s0, s1
	s_cmp_lt_u32 s0, 0x8000
	s_cbranch_scc0 .LBB0_98
	s_branch .Lxn_c
